# also skip useless trailing tile DMAs in GEMM2 last K-iteration
# speedup vs baseline: 1.0048x; 1.0006x over previous
.LBB0_448:
	v_add_u32_e32 v1, s78, v210
	ds_read_b128 v[132:135], v1
	ds_read_b128 v[136:139], v1 offset:1024
	ds_read_b128 v[140:143], v1 offset:2048
	ds_read_b128 v[144:147], v1 offset:3072
	v_add_u32_e32 v1, s79, v210
	s_add_u32 s48, s38, s46
	ds_read_b128 v[148:151], v1
	ds_read_b128 v[152:155], v1 offset:1024
	ds_read_b128 v[156:159], v1 offset:2048
	ds_read_b128 v[160:163], v1 offset:3072
	s_addc_u32 s49, s39, s47
	s_add_u32 s48, s48, 0x10000
	s_addc_u32 s49, s49, 0
	s_cmp_eq_u32 s46, 0xf0000
	s_cselect_b32 s64, s81, s48
	s_cselect_b32 s65, s21, s49
	s_cselect_b32 s50, s83, s41
	s_cselect_b32 s51, s19, s86
	s_add_u32 s48, s64, 0x8000
	s_addc_u32 s49, s65, 0
	v_lshl_add_u64 v[2:3], v[204:205], 0, s[46:47]
	s_add_i32 m0, s35, 0xc000
	ds_read_b128 v[164:167], v211
	ds_read_b128 v[168:171], v211 offset:1024
	ds_read_b128 v[172:175], v211 offset:2048
	ds_read_b128 v[176:179], v211 offset:3072
	ds_read_b128 v[180:183], v211 offset:4096
	ds_read_b128 v[184:187], v211 offset:5120
	ds_read_b128 v[212:215], v211 offset:6144
	ds_read_b128 v[216:219], v211 offset:7168
	global_load_lds_dwordx4 v[2:3], off
	v_lshl_add_u64 v[2:3], v[206:207], 0, s[46:47]
	s_add_i32 m0, s35, 0xe000
	s_nop 0
	global_load_lds_dwordx4 v[2:3], off
	s_waitcnt vmcnt(8)
	s_waitcnt lgkmcnt(0)
	s_setprio 1
	s_barrier
	v_mfma_f32_16x16x32_bf16 v[128:131], v[132:135], v[164:167], v[128:131]
	v_mfma_f32_16x16x32_bf16 v[124:127], v[140:143], v[164:167], v[124:127]
	v_mfma_f32_16x16x32_bf16 v[112:115], v[132:135], v[172:175], v[112:115]
	v_mfma_f32_16x16x32_bf16 v[108:111], v[140:143], v[172:175], v[108:111]
	v_mfma_f32_16x16x32_bf16 v[96:99], v[132:135], v[180:183], v[96:99]
	v_mfma_f32_16x16x32_bf16 v[92:95], v[140:143], v[180:183], v[92:95]
	v_mfma_f32_16x16x32_bf16 v[80:83], v[132:135], v[212:215], v[80:83]
	v_mfma_f32_16x16x32_bf16 v[76:79], v[140:143], v[212:215], v[76:79]
	v_mfma_f32_16x16x32_bf16 v[128:131], v[136:139], v[168:171], v[128:131]
	v_mfma_f32_16x16x32_bf16 v[124:127], v[144:147], v[168:171], v[124:127]
	v_mfma_f32_16x16x32_bf16 v[112:115], v[136:139], v[176:179], v[112:115]
	v_mfma_f32_16x16x32_bf16 v[108:111], v[144:147], v[176:179], v[108:111]
	v_mfma_f32_16x16x32_bf16 v[96:99], v[136:139], v[184:187], v[96:99]
	v_mfma_f32_16x16x32_bf16 v[92:95], v[144:147], v[184:187], v[92:95]
	v_mfma_f32_16x16x32_bf16 v[80:83], v[136:139], v[216:219], v[80:83]
	v_mfma_f32_16x16x32_bf16 v[76:79], v[144:147], v[216:219], v[76:79]
	v_mfma_f32_16x16x32_bf16 v[120:123], v[148:151], v[164:167], v[120:123]
	v_mfma_f32_16x16x32_bf16 v[116:119], v[156:159], v[164:167], v[116:119]
	v_mfma_f32_16x16x32_bf16 v[104:107], v[148:151], v[172:175], v[104:107]
	v_mfma_f32_16x16x32_bf16 v[100:103], v[156:159], v[172:175], v[100:103]
	v_mfma_f32_16x16x32_bf16 v[88:91], v[148:151], v[180:183], v[88:91]
	v_mfma_f32_16x16x32_bf16 v[84:87], v[156:159], v[180:183], v[84:87]
	v_mfma_f32_16x16x32_bf16 v[72:75], v[148:151], v[212:215], v[72:75]
	v_mfma_f32_16x16x32_bf16 v[68:71], v[156:159], v[212:215], v[68:71]
	v_mfma_f32_16x16x32_bf16 v[120:123], v[152:155], v[168:171], v[120:123]
	v_mfma_f32_16x16x32_bf16 v[116:119], v[160:163], v[168:171], v[116:119]
	v_mfma_f32_16x16x32_bf16 v[104:107], v[152:155], v[176:179], v[104:107]
	v_mfma_f32_16x16x32_bf16 v[100:103], v[160:163], v[176:179], v[100:103]
	v_mfma_f32_16x16x32_bf16 v[88:91], v[152:155], v[184:187], v[88:91]
	v_mfma_f32_16x16x32_bf16 v[84:87], v[160:163], v[184:187], v[84:87]
	v_mfma_f32_16x16x32_bf16 v[72:75], v[152:155], v[216:219], v[72:75]
	v_mfma_f32_16x16x32_bf16 v[68:71], v[160:163], v[216:219], v[68:71]
	s_barrier
	s_setprio 0
	s_add_i32 s88, s78, s34
	s_mov_b32 m0, s88
	ds_read_b128 v[164:167], v211 offset:16384
	ds_read_b128 v[168:171], v211 offset:17408
	ds_read_b128 v[172:175], v211 offset:18432
	ds_read_b128 v[176:179], v211 offset:19456
	ds_read_b128 v[180:183], v211 offset:20480
	ds_read_b128 v[184:187], v211 offset:21504
	ds_read_b128 v[212:215], v211 offset:22528
	ds_read_b128 v[216:219], v211 offset:23552
	s_cmp_eq_u32 s46, 0xf0000
	s_cbranch_scc1 .Lg2_last1
.Lg2_dma1:
	global_load_lds_dwordx4 v192, s[50:51]
	s_add_i32 m0, s88, 0x2000
	s_add_u32 s88, s50, 0x80000
	v_lshl_add_u64 v[222:223], s[50:51], 0, v[188:189]
	s_addc_u32 s89, s51, 0
	s_add_i32 s90, s79, s34
	global_load_lds_dwordx4 v[222:223], off
	s_mov_b32 m0, s90
	s_nop 0
	global_load_lds_dwordx4 v192, s[88:89]
	s_add_i32 m0, s90, 0x2000
	s_nop 0
	global_load_lds_dwordx4 v188, s[88:89]
	s_mov_b32 m0, s35
	s_nop 0
	global_load_lds_dwordx4 v194, s[64:65]
	s_mov_b32 m0, s56
	s_nop 0
	global_load_lds_dwordx4 v190, s[64:65]
.Lg2_join1:
	s_waitcnt vmcnt(8)
	s_waitcnt lgkmcnt(0)
	s_setprio 1
	s_barrier
	v_mfma_f32_16x16x32_bf16 v[64:67], v[132:135], v[164:167], v[64:67]
	v_mfma_f32_16x16x32_bf16 v[60:63], v[140:143], v[164:167], v[60:63]
	v_mfma_f32_16x16x32_bf16 v[48:51], v[132:135], v[172:175], v[48:51]
	v_mfma_f32_16x16x32_bf16 v[44:47], v[140:143], v[172:175], v[44:47]
	v_mfma_f32_16x16x32_bf16 v[32:35], v[132:135], v[180:183], v[32:35]
	v_mfma_f32_16x16x32_bf16 v[28:31], v[140:143], v[180:183], v[28:31]
	v_mfma_f32_16x16x32_bf16 v[16:19], v[132:135], v[212:215], v[16:19]
	v_mfma_f32_16x16x32_bf16 v[12:15], v[140:143], v[212:215], v[12:15]
	v_mfma_f32_16x16x32_bf16 v[64:67], v[136:139], v[168:171], v[64:67]
	v_mfma_f32_16x16x32_bf16 v[60:63], v[144:147], v[168:171], v[60:63]
	v_mfma_f32_16x16x32_bf16 v[48:51], v[136:139], v[176:179], v[48:51]
	v_mfma_f32_16x16x32_bf16 v[44:47], v[144:147], v[176:179], v[44:47]
	v_mfma_f32_16x16x32_bf16 v[32:35], v[136:139], v[184:187], v[32:35]
	v_mfma_f32_16x16x32_bf16 v[28:31], v[144:147], v[184:187], v[28:31]
	v_mfma_f32_16x16x32_bf16 v[16:19], v[136:139], v[216:219], v[16:19]
	v_mfma_f32_16x16x32_bf16 v[12:15], v[144:147], v[216:219], v[12:15]
	v_mfma_f32_16x16x32_bf16 v[56:59], v[148:151], v[164:167], v[56:59]
	v_mfma_f32_16x16x32_bf16 v[52:55], v[156:159], v[164:167], v[52:55]
	v_mfma_f32_16x16x32_bf16 v[40:43], v[148:151], v[172:175], v[40:43]
	v_mfma_f32_16x16x32_bf16 v[36:39], v[156:159], v[172:175], v[36:39]
	v_mfma_f32_16x16x32_bf16 v[24:27], v[148:151], v[180:183], v[24:27]
	v_mfma_f32_16x16x32_bf16 v[20:23], v[156:159], v[180:183], v[20:23]
	v_mfma_f32_16x16x32_bf16 v[8:11], v[148:151], v[212:215], v[8:11]
	v_mfma_f32_16x16x32_bf16 v[2:5], v[156:159], v[212:215], v[4:7]
	v_mfma_f32_16x16x32_bf16 v[56:59], v[152:155], v[168:171], v[56:59]
	v_mfma_f32_16x16x32_bf16 v[52:55], v[160:163], v[168:171], v[52:55]
	v_mfma_f32_16x16x32_bf16 v[40:43], v[152:155], v[176:179], v[40:43]
	v_mfma_f32_16x16x32_bf16 v[36:39], v[160:163], v[176:179], v[36:39]
	v_mfma_f32_16x16x32_bf16 v[24:27], v[152:155], v[184:187], v[24:27]
	v_mfma_f32_16x16x32_bf16 v[20:23], v[160:163], v[184:187], v[20:23]
	v_mfma_f32_16x16x32_bf16 v[8:11], v[152:155], v[216:219], v[8:11]
	v_mfma_f32_16x16x32_bf16 v[2:5], v[160:163], v[216:219], v[2:5]
	s_barrier
	s_setprio 0
	s_add_i32 s88, 0, 0x18000
	v_add_u32_e32 v1, s88, v210
	s_add_i32 s89, 0, 0x1c000
	ds_read_b128 v[132:135], v1
	ds_read_b128 v[136:139], v1 offset:1024
	ds_read_b128 v[140:143], v1 offset:2048
	ds_read_b128 v[144:147], v1 offset:3072
	v_add_u32_e32 v1, s89, v210
	ds_read_b128 v[148:151], v1
	ds_read_b128 v[152:155], v1 offset:1024
	ds_read_b128 v[156:159], v1 offset:2048
	ds_read_b128 v[160:163], v1 offset:3072
	s_add_u32 s64, s64, 0x2000
	s_addc_u32 s65, s65, 0
	s_mov_b32 m0, s57
	ds_read_b128 v[164:167], v211 offset:32768
	ds_read_b128 v[168:171], v211 offset:33792
	ds_read_b128 v[172:175], v211 offset:34816
	ds_read_b128 v[176:179], v211 offset:35840
	ds_read_b128 v[180:183], v211 offset:36864
	ds_read_b128 v[184:187], v211 offset:37888
	ds_read_b128 v[212:215], v211 offset:38912
	ds_read_b128 v[216:219], v211 offset:39936
	s_cmp_eq_u32 s46, 0xf0000
	s_cbranch_scc1 .Lg2_last2
.Lg2_dma2:
	global_load_lds_dwordx4 v194, s[64:65]
	s_mov_b32 m0, s59
	s_nop 0
	global_load_lds_dwordx4 v190, s[64:65]
.Lg2_join2:
	s_waitcnt vmcnt(8)
	s_waitcnt lgkmcnt(0)
	s_setprio 1
	s_barrier
	v_mfma_f32_16x16x32_bf16 v[128:131], v[132:135], v[164:167], v[128:131]
	v_mfma_f32_16x16x32_bf16 v[124:127], v[140:143], v[164:167], v[124:127]
	v_mfma_f32_16x16x32_bf16 v[112:115], v[132:135], v[172:175], v[112:115]
	v_mfma_f32_16x16x32_bf16 v[108:111], v[140:143], v[172:175], v[108:111]
	v_mfma_f32_16x16x32_bf16 v[96:99], v[132:135], v[180:183], v[96:99]
	v_mfma_f32_16x16x32_bf16 v[92:95], v[140:143], v[180:183], v[92:95]
	v_mfma_f32_16x16x32_bf16 v[80:83], v[132:135], v[212:215], v[80:83]
	v_mfma_f32_16x16x32_bf16 v[76:79], v[140:143], v[212:215], v[76:79]
	v_mfma_f32_16x16x32_bf16 v[128:131], v[136:139], v[168:171], v[128:131]
	v_mfma_f32_16x16x32_bf16 v[124:127], v[144:147], v[168:171], v[124:127]
	v_mfma_f32_16x16x32_bf16 v[112:115], v[136:139], v[176:179], v[112:115]
	v_mfma_f32_16x16x32_bf16 v[108:111], v[144:147], v[176:179], v[108:111]
	v_mfma_f32_16x16x32_bf16 v[96:99], v[136:139], v[184:187], v[96:99]
	v_mfma_f32_16x16x32_bf16 v[92:95], v[144:147], v[184:187], v[92:95]
	v_mfma_f32_16x16x32_bf16 v[80:83], v[136:139], v[216:219], v[80:83]
	v_mfma_f32_16x16x32_bf16 v[76:79], v[144:147], v[216:219], v[76:79]
	v_mfma_f32_16x16x32_bf16 v[120:123], v[148:151], v[164:167], v[120:123]
	v_mfma_f32_16x16x32_bf16 v[116:119], v[156:159], v[164:167], v[116:119]
	v_mfma_f32_16x16x32_bf16 v[104:107], v[148:151], v[172:175], v[104:107]
	v_mfma_f32_16x16x32_bf16 v[100:103], v[156:159], v[172:175], v[100:103]
	v_mfma_f32_16x16x32_bf16 v[88:91], v[148:151], v[180:183], v[88:91]
	v_mfma_f32_16x16x32_bf16 v[84:87], v[156:159], v[180:183], v[84:87]
	v_mfma_f32_16x16x32_bf16 v[72:75], v[148:151], v[212:215], v[72:75]
	v_mfma_f32_16x16x32_bf16 v[68:71], v[156:159], v[212:215], v[68:71]
	v_mfma_f32_16x16x32_bf16 v[120:123], v[152:155], v[168:171], v[120:123]
	v_mfma_f32_16x16x32_bf16 v[116:119], v[160:163], v[168:171], v[116:119]
	v_mfma_f32_16x16x32_bf16 v[104:107], v[152:155], v[176:179], v[104:107]
	v_mfma_f32_16x16x32_bf16 v[100:103], v[160:163], v[176:179], v[100:103]
	v_mfma_f32_16x16x32_bf16 v[88:91], v[152:155], v[184:187], v[88:91]
	v_mfma_f32_16x16x32_bf16 v[84:87], v[160:163], v[184:187], v[84:87]
	v_mfma_f32_16x16x32_bf16 v[72:75], v[152:155], v[216:219], v[72:75]
	v_mfma_f32_16x16x32_bf16 v[68:71], v[160:163], v[216:219], v[68:71]
	s_barrier
	s_setprio 0
	s_add_u32 s98, s50, s10
	s_addc_u32 s99, s51, s11
	s_add_i32 s64, s88, s34
	s_mov_b32 m0, s64
	ds_read_b128 v[164:167], v211 offset:49152
	ds_read_b128 v[168:171], v211 offset:50176
	ds_read_b128 v[172:175], v211 offset:51200
	ds_read_b128 v[176:179], v211 offset:52224
	ds_read_b128 v[180:183], v211 offset:53248
	ds_read_b128 v[184:187], v211 offset:54272
	ds_read_b128 v[212:215], v211 offset:55296
	ds_read_b128 v[216:219], v211 offset:56320
	s_cmp_eq_u32 s46, 0xf0000
	s_cbranch_scc1 .Lg2_last3
.Lg2_dma3:
	global_load_lds_dwordx4 v192, s[98:99]
	s_add_i32 m0, s64, 0x2000
	s_add_u32 s50, s50, 0x80080
	v_lshl_add_u64 v[6:7], v[222:223], 0, s[10:11]
	s_addc_u32 s51, s51, 0
	s_add_i32 s64, s89, s34
	global_load_lds_dwordx4 v[6:7], off
	s_mov_b32 m0, s64
	s_nop 0
	global_load_lds_dwordx4 v192, s[50:51]
	s_add_i32 m0, s64, 0x2000
	s_nop 0
	global_load_lds_dwordx4 v188, s[50:51]
	s_mov_b32 m0, s74
	s_nop 0
	global_load_lds_dwordx4 v194, s[48:49]
	s_mov_b32 m0, s75
	s_nop 0
	global_load_lds_dwordx4 v190, s[48:49]
.Lg2_join3:
	s_waitcnt vmcnt(8)
	s_waitcnt lgkmcnt(0)
	s_setprio 1
	s_barrier
	v_mfma_f32_16x16x32_bf16 v[64:67], v[132:135], v[164:167], v[64:67]
	v_mfma_f32_16x16x32_bf16 v[60:63], v[140:143], v[164:167], v[60:63]
	v_mfma_f32_16x16x32_bf16 v[48:51], v[132:135], v[172:175], v[48:51]
	v_mfma_f32_16x16x32_bf16 v[44:47], v[140:143], v[172:175], v[44:47]
	v_mfma_f32_16x16x32_bf16 v[32:35], v[132:135], v[180:183], v[32:35]
	v_mfma_f32_16x16x32_bf16 v[28:31], v[140:143], v[180:183], v[28:31]
	v_mfma_f32_16x16x32_bf16 v[16:19], v[132:135], v[212:215], v[16:19]
	v_mfma_f32_16x16x32_bf16 v[12:15], v[140:143], v[212:215], v[12:15]
	v_mfma_f32_16x16x32_bf16 v[64:67], v[136:139], v[168:171], v[64:67]
	v_mfma_f32_16x16x32_bf16 v[60:63], v[144:147], v[168:171], v[60:63]
	v_mfma_f32_16x16x32_bf16 v[48:51], v[136:139], v[176:179], v[48:51]
	v_mfma_f32_16x16x32_bf16 v[44:47], v[144:147], v[176:179], v[44:47]
	v_mfma_f32_16x16x32_bf16 v[32:35], v[136:139], v[184:187], v[32:35]
	v_mfma_f32_16x16x32_bf16 v[28:31], v[144:147], v[184:187], v[28:31]
	v_mfma_f32_16x16x32_bf16 v[16:19], v[136:139], v[216:219], v[16:19]
	v_mfma_f32_16x16x32_bf16 v[12:15], v[144:147], v[216:219], v[12:15]
	v_mfma_f32_16x16x32_bf16 v[56:59], v[148:151], v[164:167], v[56:59]
	v_mfma_f32_16x16x32_bf16 v[52:55], v[156:159], v[164:167], v[52:55]
	v_mfma_f32_16x16x32_bf16 v[40:43], v[148:151], v[172:175], v[40:43]
	v_mfma_f32_16x16x32_bf16 v[36:39], v[156:159], v[172:175], v[36:39]
	v_mfma_f32_16x16x32_bf16 v[24:27], v[148:151], v[180:183], v[24:27]
	v_mfma_f32_16x16x32_bf16 v[20:23], v[156:159], v[180:183], v[20:23]
	v_mfma_f32_16x16x32_bf16 v[6:9], v[148:151], v[212:215], v[8:11]
	v_mfma_f32_16x16x32_bf16 v[2:5], v[156:159], v[212:215], v[2:5]
	v_mfma_f32_16x16x32_bf16 v[56:59], v[152:155], v[168:171], v[56:59]
	v_mfma_f32_16x16x32_bf16 v[52:55], v[160:163], v[168:171], v[52:55]
	v_mfma_f32_16x16x32_bf16 v[40:43], v[152:155], v[176:179], v[40:43]
	v_mfma_f32_16x16x32_bf16 v[36:39], v[160:163], v[176:179], v[36:39]
	v_mfma_f32_16x16x32_bf16 v[24:27], v[152:155], v[184:187], v[24:27]
	v_mfma_f32_16x16x32_bf16 v[20:23], v[160:163], v[184:187], v[20:23]
	v_mfma_f32_16x16x32_bf16 v[8:11], v[152:155], v[216:219], v[6:9]
	v_mfma_f32_16x16x32_bf16 v[4:7], v[160:163], v[216:219], v[2:5]
	s_barrier
	s_setprio 0
	s_add_i32 s87, s87, 2
	s_add_u32 s41, s41, 0x100
	s_addc_u32 s86, s86, 0
	s_add_u32 s46, s46, 0x10000
	s_addc_u32 s47, s47, 0
	s_cmp_gt_u32 s87, 29
	s_cbranch_scc1 .LBB0_440

.Lg2_last1:
	s_cmp_eq_u32 s4, 0
	s_cbranch_scc1 .Lg2_dma1
	s_add_i32 m0, s88, 0x2000
	s_add_u32 s88, s50, 0x80000
	v_lshl_add_u64 v[222:223], s[50:51], 0, v[188:189]
	s_addc_u32 s89, s51, 0
	s_add_i32 s90, s79, s34
	s_mov_b32 m0, s90
	s_add_i32 m0, s90, 0x2000
	s_mov_b32 m0, s35
	s_mov_b32 m0, s56
	s_waitcnt vmcnt(2)
	s_branch .Lg2_join1

.Lg2_last3:
	s_cmp_eq_u32 s4, 0
	s_cbranch_scc1 .Lg2_dma3
	s_add_i32 m0, s64, 0x2000
	s_add_u32 s50, s50, 0x80080
	v_lshl_add_u64 v[6:7], v[222:223], 0, s[10:11]
	s_addc_u32 s51, s51, 0
	s_add_i32 s64, s89, s34
	s_mov_b32 m0, s64
	s_add_i32 m0, s64, 0x2000
	s_mov_b32 m0, s74
	s_mov_b32 m0, s75
	s_branch .Lg2_join3
